# nt hint on the P6 epilogue residual-x loads (read once; keeps L2 for H1/X1B), on top of all row-store exchanges
# speedup vs baseline: 1.0181x; 1.0181x over previous
.LBB0_1482:
	s_lshr_b32 s17, s46, 4
	s_mul_i32 s48, s17, 0xc00
	s_ashr_i32 s49, s48, 31
	v_lshl_or_b32 v208, s44, 8, v230
	s_lshl_b64 s[48:49], s[48:49], 2
	s_add_u32 s50, s78, s48
	v_ashrrev_i32_e32 v209, 31, v208
	s_addc_u32 s51, s79, s49
	v_lshlrev_b64 v[216:217], 2, v[208:209]
	v_lshl_add_u32 v218, s46, 8, v228
	v_lshl_add_u64 v[112:113], s[50:51], 0, v[216:217]
	s_mov_b64 s[50:51], 0x1502000
	s_mov_b32 s17, 0x1502000
	v_ashrrev_i32_e32 v219, 31, v218
	v_lshl_add_u64 v[114:115], v[112:113], 0, s[50:51]
	v_add_co_u32_e32 v112, vcc, s17, v112
	v_lshl_add_u64 v[220:221], s[52:53], 0, v[216:217]
	v_lshlrev_b64 v[116:117], 12, v[218:219]
	v_addc_co_u32_e32 v113, vcc, 0, v113, vcc
	v_lshl_add_u64 v[144:145], v[220:221], 0, v[116:117]
	global_load_dwordx4 v[224:227], v[144:145], off offset:16 nt
	global_load_dwordx4 v[124:127], v[114:115], off offset:16
	global_load_dwordx4 v[116:119], v[114:115], off offset:512
	global_load_dwordx4 v[240:243], v[144:145], off offset:512 nt
	global_load_dwordx4 v[128:131], v[112:113], off
	global_load_dwordx4 v[244:247], v[144:145], off nt
	global_load_dwordx4 v[248:251], v[144:145], off offset:528 nt
	s_nop 0
	global_load_dwordx4 v[112:115], v[114:115], off offset:528
	v_or_b32_e32 v210, 16, v218
	v_ashrrev_i32_e32 v211, 31, v210
	v_lshlrev_b64 v[144:145], 12, v[210:211]
	v_or_b32_e32 v214, 32, v218
	v_lshl_add_u64 v[144:145], v[220:221], 0, v[144:145]
	v_ashrrev_i32_e32 v215, 31, v214
	global_load_dwordx4 v[184:187], v[144:145], off offset:16 nt
	global_load_dwordx4 v[188:191], v[144:145], off nt
	global_load_dwordx4 v[172:175], v[144:145], off offset:528 nt
	global_load_dwordx4 v[176:179], v[144:145], off offset:512 nt
	v_lshlrev_b64 v[144:145], 12, v[214:215]
	v_or_b32_e32 v222, 48, v218
	v_lshl_add_u64 v[144:145], v[220:221], 0, v[144:145]
	v_ashrrev_i32_e32 v223, 31, v222
	global_load_dwordx4 v[168:171], v[144:145], off offset:16 nt
	global_load_dwordx4 v[180:183], v[144:145], off nt
	global_load_dwordx4 v[160:163], v[144:145], off offset:528 nt
	global_load_dwordx4 v[164:167], v[144:145], off offset:512 nt
	v_lshlrev_b64 v[144:145], 12, v[222:223]
	v_lshl_add_u64 v[148:149], v[220:221], 0, v[144:145]
	global_load_dwordx4 v[152:155], v[148:149], off offset:16 nt
	global_load_dwordx4 v[156:159], v[148:149], off nt
	global_load_dwordx4 v[144:147], v[148:149], off offset:528 nt
	s_nop 0
	global_load_dwordx4 v[148:151], v[148:149], off offset:512 nt
	v_and_b32_e32 v212, 64, v236
	v_xor_b32_e32 v238, 16, v236
	v_add_u32_e32 v252, 64, v212
	v_cmp_lt_i32_e32 vcc, v238, v252
	v_xor_b32_e32 v239, 32, v236
	v_lshlrev_b64 v[212:213], 11, v[218:219]
	v_cndmask_b32_e32 v238, v236, v238, vcc
	v_lshlrev_b32_e32 v238, 2, v238
	v_cmp_lt_i32_e32 vcc, v239, v252
	v_lshl_add_u64 v[252:253], s[6:7], 0, v[212:213]
	v_lshl_add_u64 v[252:253], v[208:209], 1, v[252:253]
	v_cndmask_b32_e32 v239, v236, v239, vcc
	v_lshlrev_b32_e32 v239, 2, v239
	s_waitcnt vmcnt(0)
	v_pk_fma_f32 v[138:139], v[138:139], v[126:127], v[226:227]
	v_pk_fma_f32 v[136:137], v[136:137], v[124:125], v[224:225]
	v_pk_fma_f32 v[226:227], v[8:9], v[116:117], v[240:241]
	v_pk_fma_f32 v[224:225], v[10:11], v[118:119], v[242:243]
	v_pk_fma_f32 v[140:141], v[140:141], v[128:129], v[244:245]
	v_pk_fma_f32 v[10:11], v[142:143], v[130:131], v[246:247]
	v_pk_fma_f32 v[142:143], v[6:7], v[114:115], v[250:251]
	v_pk_fma_f32 v[6:7], v[4:5], v[112:113], v[248:249]
	v_and_b32_e32 v244, 15, v228
	v_lshrrev_b32_e32 v245, 6, v228
	v_lshl_add_u32 v246, v245, 4, v244
	v_mul_u32_u24_e32 v246, 0x210, v246
	v_lshrrev_b32_e32 v247, 3, v230
	v_lshl_add_u32 v246, v247, 4, v246
	v_add_u32_e32 v240, 0x21000, v246
	v_lshrrev_b32_e32 v247, 5, v230
	v_lshrrev_b32_e32 v248, 5, v236
	v_lshl_add_u32 v247, v247, 2, v248
	v_lshl_add_u32 v248, v245, 4, v247
	v_mul_u32_u24_e32 v248, 0x210, v248
	v_and_b32_e32 v249, 31, v236
	v_lshl_add_u32 v248, v249, 4, v248
	v_add_u32_e32 v241, 0x21000, v248
	v_sub_u32_e32 v250, v247, v244
	v_lshlrev_b32_e32 v250, 11, v250
	v_lshlrev_b32_e32 v249, 3, v249
	v_sub_u32_e32 v249, v249, v230
	v_lshl_add_u32 v242, v249, 1, v250
	v_add_u32_e32 v242, 0x800, v242
	v_ashrrev_i32_e32 v243, 31, v242
	v_mul_f32_e32 v4, v227, v227
	v_mul_f32_e32 v5, v141, v141
	v_fmac_f32_e32 v4, v226, v226
	v_fmac_f32_e32 v5, v140, v140
	v_fmac_f32_e32 v4, v224, v224
	v_fmac_f32_e32 v5, v10, v10
	v_fmac_f32_e32 v4, v225, v225
	v_fmac_f32_e32 v5, v11, v11
	v_fmac_f32_e32 v4, v6, v6
	v_fmac_f32_e32 v5, v136, v136
	v_fmac_f32_e32 v4, v7, v7
	v_fmac_f32_e32 v5, v137, v137
	v_fmac_f32_e32 v4, v142, v142
	v_fmac_f32_e32 v5, v138, v138
	v_fmac_f32_e32 v4, v143, v143
	v_fmac_f32_e32 v5, v139, v139
	v_add_f32_e32 v5, v5, v4
	v_cvt_pk_bf16_f32 v8, v140, v141
	ds_bpermute_b32 v140, v238, v5
	v_cvt_pk_bf16_f32 v9, v10, v11
	v_cvt_pk_bf16_f32 v10, v136, v137
	v_cvt_pk_bf16_f32 v11, v138, v139
	ds_write_b128 v240, v[8:11]
	s_waitcnt lgkmcnt(0)
	v_add_f32_e32 v136, v5, v140
	ds_bpermute_b32 v137, v239, v136
	v_cvt_pk_bf16_f32 v4, v226, v227
	v_cvt_pk_bf16_f32 v5, v224, v225
	v_cvt_pk_bf16_f32 v6, v6, v7
	v_cvt_pk_bf16_f32 v7, v142, v143
	ds_write_b128 v240, v[4:7] offset:256
	v_lshl_add_u64 v[252:253], v[252:253], 0, v[242:243]
	s_waitcnt lgkmcnt(0)
	s_barrier
	ds_read_b128 v[244:247], v241
	ds_read_b128 v[248:251], v241 offset:1056
	s_waitcnt lgkmcnt(0)
	s_barrier
	global_store_dwordx4 v[252:253], v[244:247], off offset:-2048
	global_store_dwordx4 v[252:253], v[248:251], off offset:2048
	s_and_saveexec_b64 s[50:51], s[0:1]
	s_cbranch_execz .LBB0_1484
	s_waitcnt lgkmcnt(0)
	v_add_f32_e32 v136, v136, v137
	ds_write_b32 v231, v136

.LBB0_1486:
	s_or_b64 exec, exec, s[50:51]
	v_add_u32_e32 v226, 0x80, v218
	v_ashrrev_i32_e32 v227, 31, v226
	s_waitcnt lgkmcnt(0)
	v_lshlrev_b64 v[120:121], 12, v[226:227]
	v_add_u32_e32 v224, 0x90, v218
	v_lshl_add_u64 v[120:121], v[220:221], 0, v[120:121]
	v_ashrrev_i32_e32 v225, 31, v224
	global_load_dwordx4 v[184:187], v[120:121], off offset:16 nt
	global_load_dwordx4 v[188:191], v[120:121], off nt
	global_load_dwordx4 v[172:175], v[120:121], off offset:528 nt
	global_load_dwordx4 v[176:179], v[120:121], off offset:512 nt
	v_lshlrev_b64 v[120:121], 12, v[224:225]
	v_lshl_add_u64 v[132:133], v[220:221], 0, v[120:121]
	global_load_dwordx4 v[136:139], v[132:133], off offset:16 nt
	global_load_dwordx4 v[140:143], v[132:133], off nt
	global_load_dwordx4 v[120:123], v[132:133], off offset:528 nt
	s_nop 0
	global_load_dwordx4 v[132:135], v[132:133], off offset:512 nt
	v_pk_fma_f32 v[108:109], v[108:109], v[128:129], v[180:181]
	v_pk_fma_f32 v[104:105], v[104:105], v[116:117], v[164:165]
	v_mul_f32_e32 v180, v109, v109
	v_pk_fma_f32 v[168:169], v[16:17], v[124:125], v[168:169]
	v_cvt_pk_bf16_f32 v16, v108, v109
	v_fmac_f32_e32 v180, v108, v108
	v_pk_fma_f32 v[108:109], v[26:27], v[114:115], v[162:163]
	v_pk_fma_f32 v[26:27], v[24:25], v[112:113], v[160:161]
	v_mul_f32_e32 v24, v105, v105
	v_pk_fma_f32 v[110:111], v[110:111], v[130:131], v[182:183]
	v_pk_fma_f32 v[106:107], v[106:107], v[118:119], v[166:167]
	v_fmac_f32_e32 v24, v104, v104
	v_fmac_f32_e32 v180, v110, v110
	v_fmac_f32_e32 v24, v106, v106
	v_fmac_f32_e32 v180, v111, v111
	v_fmac_f32_e32 v24, v107, v107
	v_fmac_f32_e32 v180, v168, v168
	v_fmac_f32_e32 v24, v26, v26
	v_pk_fma_f32 v[170:171], v[18:19], v[126:127], v[170:171]
	v_fmac_f32_e32 v180, v169, v169
	v_fmac_f32_e32 v24, v27, v27
	v_fmac_f32_e32 v180, v170, v170
	v_fmac_f32_e32 v24, v108, v108
	v_fmac_f32_e32 v180, v171, v171
	v_fmac_f32_e32 v24, v109, v109
	v_add_f32_e32 v160, v180, v24
	ds_bpermute_b32 v161, v238, v160
	v_lshlrev_b64 v[214:215], 11, v[214:215]
	v_lshl_add_u64 v[24:25], s[6:7], 0, v[214:215]
	v_cvt_pk_bf16_f32 v17, v110, v111
	v_lshl_add_u64 v[110:111], v[208:209], 1, v[24:25]
	v_cvt_pk_bf16_f32 v18, v168, v169
	v_cvt_pk_bf16_f32 v19, v170, v171
	ds_write_b128 v240, v[16:19]
	v_cvt_pk_bf16_f32 v24, v104, v105
	s_waitcnt lgkmcnt(0)
	v_add_f32_e32 v104, v160, v161
	ds_bpermute_b32 v105, v239, v104
	v_cvt_pk_bf16_f32 v25, v106, v107
	v_cvt_pk_bf16_f32 v26, v26, v27
	v_cvt_pk_bf16_f32 v27, v108, v109
	ds_write_b128 v240, v[24:27] offset:256
	v_lshl_add_u64 v[252:253], v[110:111], 0, v[242:243]
	s_waitcnt lgkmcnt(0)
	s_barrier
	ds_read_b128 v[244:247], v241
	ds_read_b128 v[248:251], v241 offset:1056
	s_waitcnt lgkmcnt(0)
	s_barrier
	global_store_dwordx4 v[252:253], v[244:247], off offset:-2048
	global_store_dwordx4 v[252:253], v[248:251], off offset:2048
	s_and_saveexec_b64 s[50:51], s[0:1]
	s_cbranch_execz .LBB0_1488
	s_waitcnt lgkmcnt(0)
	v_add_f32_e32 v104, v104, v105
	ds_write_b32 v231, v104 offset:128

.LBB0_1490:
	s_or_b64 exec, exec, s[50:51]
	v_or_b32_e32 v96, 32, v226
	s_waitcnt lgkmcnt(0)
	v_ashrrev_i32_e32 v97, 31, v96
	v_lshlrev_b64 v[96:97], 12, v[96:97]
	v_add_u32_e32 v166, 0xb0, v218
	v_lshl_add_u64 v[96:97], v[220:221], 0, v[96:97]
	v_ashrrev_i32_e32 v167, 31, v166
	global_load_dwordx4 v[152:155], v[96:97], off offset:16 nt
	global_load_dwordx4 v[156:159], v[96:97], off nt
	global_load_dwordx4 v[144:147], v[96:97], off offset:528 nt
	global_load_dwordx4 v[148:151], v[96:97], off offset:512 nt
	v_lshlrev_b64 v[96:97], 12, v[166:167]
	v_lshl_add_u64 v[100:101], v[220:221], 0, v[96:97]
	global_load_dwordx4 v[104:107], v[100:101], off offset:16 nt
	global_load_dwordx4 v[108:111], v[100:101], off nt
	global_load_dwordx4 v[96:99], v[100:101], off offset:528 nt
	s_nop 0
	global_load_dwordx4 v[100:103], v[100:101], off offset:512 nt
	s_waitcnt vmcnt(18)
	v_pk_fma_f32 v[92:93], v[92:93], v[128:129], v[188:189]
	s_waitcnt vmcnt(16)
	v_pk_fma_f32 v[88:89], v[88:89], v[116:117], v[176:177]
	v_mul_f32_e32 v170, v93, v93
	v_pk_fma_f32 v[168:169], v[32:33], v[124:125], v[184:185]
	v_cvt_pk_bf16_f32 v32, v92, v93
	v_fmac_f32_e32 v170, v92, v92
	v_pk_fma_f32 v[92:93], v[50:51], v[114:115], v[174:175]
	v_pk_fma_f32 v[50:51], v[48:49], v[112:113], v[172:173]
	v_mul_f32_e32 v48, v89, v89
	v_pk_fma_f32 v[94:95], v[94:95], v[130:131], v[190:191]
	v_pk_fma_f32 v[90:91], v[90:91], v[118:119], v[178:179]
	v_fmac_f32_e32 v48, v88, v88
	v_fmac_f32_e32 v170, v94, v94
	v_fmac_f32_e32 v48, v90, v90
	v_fmac_f32_e32 v170, v95, v95
	v_fmac_f32_e32 v48, v91, v91
	v_fmac_f32_e32 v170, v168, v168
	v_fmac_f32_e32 v48, v50, v50
	v_pk_fma_f32 v[164:165], v[34:35], v[126:127], v[186:187]
	v_fmac_f32_e32 v170, v169, v169
	v_fmac_f32_e32 v48, v51, v51
	v_fmac_f32_e32 v170, v164, v164
	v_fmac_f32_e32 v48, v92, v92
	v_fmac_f32_e32 v170, v165, v165
	v_fmac_f32_e32 v48, v93, v93
	v_cvt_pk_bf16_f32 v33, v94, v95
	v_cvt_pk_bf16_f32 v34, v168, v169
	v_cvt_pk_bf16_f32 v35, v164, v165
	v_add_f32_e32 v164, v170, v48
	ds_bpermute_b32 v165, v238, v164
	v_lshlrev_b64 v[162:163], 11, v[226:227]
	v_lshl_add_u64 v[48:49], s[6:7], 0, v[162:163]
	v_lshl_add_u64 v[94:95], v[208:209], 1, v[48:49]
	ds_write_b128 v240, v[32:35]
	v_cvt_pk_bf16_f32 v48, v88, v89
	s_waitcnt lgkmcnt(0)
	v_add_f32_e32 v88, v164, v165
	ds_bpermute_b32 v89, v239, v88
	v_cvt_pk_bf16_f32 v49, v90, v91
	v_cvt_pk_bf16_f32 v50, v50, v51
	v_cvt_pk_bf16_f32 v51, v92, v93
	ds_write_b128 v240, v[48:51] offset:256
	v_lshl_add_u64 v[252:253], v[94:95], 0, v[242:243]
	s_waitcnt lgkmcnt(0)
	s_barrier
	ds_read_b128 v[244:247], v241
	ds_read_b128 v[248:251], v241 offset:1056
	s_waitcnt lgkmcnt(0)
	s_barrier
	global_store_dwordx4 v[252:253], v[244:247], off offset:-2048
	global_store_dwordx4 v[252:253], v[248:251], off offset:2048
	s_and_saveexec_b64 s[50:51], s[0:1]
	s_cbranch_execz .LBB0_1492
	s_waitcnt lgkmcnt(0)
	v_add_f32_e32 v88, v88, v89
	ds_write_b32 v231, v88 offset:256
